# attention epilogue: permlane32_swap pairs -> 8 dwordx4 stores instead of 16 dwordx2 (store-issue-bound tail)
# speedup vs baseline: 1.0051x; 1.0051x over previous
; #define LAS __attribute__((address_space(3)))
; __device__ __forceinline__ unsigned pk2(float lo, float hi) { const f32x2_t f = {lo, hi}; const bf16x2_t b = __builtin_convertvector(f, bf16x2_t); return __builtin_bit_cast(unsigned, b); }
; __device__ __forceinline__ void attn_item(const Params& P, int slice, int item, LAS unsigned char* lds) {
;     ...
;   const float inv = 1.0f / den;
;   if (h == 0) ((float*)(ws + O_LSE))[((size_t)(gi * 4 + g)) * TS + b * L + r * M + mq] = mx + __logf(den);
;   __syncthreads();
;   stage_kv(qkv + 3072 + head * 128, b, L, dil, r, m0, M, img, nullptr, ht);
;   __syncthreads();
;   f32x16 oa[4];
; #pragma unroll
;   for (int dt = 0; dt < 4; ++dt)
; #pragma unroll
;     for (int i = 0; i < 16; ++i) oa[dt][i] = 0.f;
;   const int i16 = lane & 15, q4 = i16 >> 2, p4 = i16 & 3, blk = (lane >> 4) & 1;
; #pragma unroll
;   for (int kt = 0; kt < 5; ++kt)
; #pragma unroll
;     for (int s = 0; s < 2; ++s) {
;       u32x4 pb; pb.x = pk2(sc[kt][8 * s + 0] * inv, sc[kt][8 * s + 1] * inv); pb.y = pk2(sc[kt][8 * s + 2] * inv, sc[kt][8 * s + 3] * inv);
;       pb.z = pk2(sc[kt][8 * s + 4] * inv, sc[kt][8 * s + 5] * inv); pb.w = pk2(sc[kt][8 * s + 6] * inv, sc[kt][8 * s + 7] * inv);
;       const bf16x8 bfr = __builtin_bit_cast(bf16x8, pb);
;       const LAS unsigned char* vp = img + (32 * wq + 32 * kt + 16 * s + 4 * h + q4) * KROW + 2 * (16 * blk + 4 * p4);
; #pragma unroll
;       for (int dt = 0; dt < 4; ++dt) {
;         const s16x4 lo = __builtin_amdgcn_ds_read_tr16_b64_v4i16((LAS s16x4*)(vp + 64 * dt));
;         const s16x4 hi4 = __builtin_amdgcn_ds_read_tr16_b64_v4i16((LAS s16x4*)(vp + 64 * dt + 8 * KROW));
;         const bf16x8 a = __builtin_shufflevector(lo, hi4, 0, 1, 2, 3, 4, 5, 6, 7);
;         oa[dt] = __builtin_amdgcn_mfma_f32_32x32x16_bf16(a, bfr, oa[dt], 0, 0, 0);
;       }
;     }
.LBB0_380:
	s_or_b64 exec, exec, s[0:1]
	v_div_scale_f32 v0, s[0:1], v65, v65, 1.0
	v_rcp_f32_e32 v2, v0
	v_div_scale_f32 v3, vcc, 1.0, v65, 1.0
	s_ashr_i32 s83, s82, 31
	v_fma_f32 v5, -v0, v2, 1.0
	v_fmac_f32_e32 v2, v5, v2
	v_mul_f32_e32 v5, v3, v2
	v_fma_f32 v8, -v0, v5, v3
	v_fmac_f32_e32 v5, v8, v2
	v_fma_f32 v0, -v0, v5, v3
	v_div_fmas_f32 v0, v0, v2, v5
	v_div_fixup_f32 v80, v0, v65, 1.0
	v_mov_b32_e32 v5, v1
	v_bfe_u32 v0, v107, 2, 2
	v_and_b32_e32 v1, 16, v107
	v_lshlrev_b32_e32 v2, 2, v107
	v_or3_b32 v0, v0, v168, s72
	v_and_or_b32 v1, v2, 12, v1
	v_lshlrev_b32_e32 v1, 1, v1
	v_mul_u32_u24_e32 v0, 0x110, v0
	v_add3_u32 v152, s64, v1, v0
	ds_write_b128 v154, v[4:7] offset:65280
	s_waitcnt lgkmcnt(0)
	s_barrier
	ds_read_b64_tr_b16 v[0:1], v152
	ds_read_b64_tr_b16 v[2:3], v152 offset:2176
	v_pk_mul_f32 v[4:5], v[76:77], v[80:81] op_sel_hi:[1,0]
	v_pk_mul_f32 v[64:65], v[66:67], v[80:81] op_sel_hi:[1,0]
	v_cvt_pk_bf16_f32 v16, v4, v5
	v_pk_mul_f32 v[4:5], v[78:79], v[80:81] op_sel_hi:[1,0]
	v_pk_mul_f32 v[66:67], v[68:69], v[80:81] op_sel_hi:[1,0]
	v_cvt_pk_bf16_f32 v17, v4, v5
	v_pk_mul_f32 v[4:5], v[84:85], v[80:81] op_sel_hi:[1,0]
	v_cvt_pk_bf16_f32 v64, v64, v65
	v_cvt_pk_bf16_f32 v18, v4, v5
	v_pk_mul_f32 v[4:5], v[90:91], v[80:81] op_sel_hi:[1,0]
	v_cvt_pk_bf16_f32 v65, v66, v67
	v_cvt_pk_bf16_f32 v19, v4, v5
	v_pk_mul_f32 v[66:67], v[70:71], v[80:81] op_sel_hi:[1,0]
	v_pk_mul_f32 v[68:69], v[74:75], v[80:81] op_sel_hi:[1,0]
	s_waitcnt lgkmcnt(0)
	v_mfma_f32_32x32x16_bf16 v[48:63], v[0:3], v[16:19], 0
	ds_read_b64_tr_b16 v[0:1], v152 offset:64
	ds_read_b64_tr_b16 v[2:3], v152 offset:2240
	v_cvt_pk_bf16_f32 v66, v66, v67
	v_cvt_pk_bf16_f32 v67, v68, v69
	s_lshl_b64 s[0:1], s[82:83], 24
	v_ashrrev_i32_e32 v107, 31, v106
	s_add_u32 s0, s4, s0
	s_addc_u32 s1, s5, s1
	s_waitcnt lgkmcnt(0)
	v_mfma_f32_32x32x16_bf16 v[32:47], v[0:3], v[16:19], 0
	ds_read_b64_tr_b16 v[0:1], v152 offset:128
	ds_read_b64_tr_b16 v[2:3], v152 offset:2304
	ds_read_b64_tr_b16 v[20:21], v152 offset:192
	ds_read_b64_tr_b16 v[22:23], v152 offset:2368
	ds_read_b64_tr_b16 v[76:77], v152 offset:4352
	ds_read_b64_tr_b16 v[78:79], v152 offset:6528
	ds_read_b64_tr_b16 v[68:69], v152 offset:4416
	ds_read_b64_tr_b16 v[70:71], v152 offset:6592
	s_lshl_b32 s64, s3, 8
	s_waitcnt lgkmcnt(6)
	v_mfma_f32_32x32x16_bf16 v[0:15], v[0:3], v[16:19], 0
	s_waitcnt lgkmcnt(0)
	v_mfma_f32_32x32x16_bf16 v[32:47], v[68:71], v[64:67], v[32:47]
	ds_read_b64_tr_b16 v[68:69], v152 offset:4480
	ds_read_b64_tr_b16 v[70:71], v152 offset:6656
	v_mfma_f32_32x32x16_bf16 v[16:31], v[20:23], v[16:19], 0
	s_waitcnt lgkmcnt(0)
	v_mfma_f32_32x32x16_bf16 v[0:15], v[68:71], v[64:67], v[0:15]
	ds_read_b64_tr_b16 v[68:69], v152 offset:4544
	ds_read_b64_tr_b16 v[70:71], v152 offset:6720
	v_mfma_f32_32x32x16_bf16 v[48:63], v[76:79], v[64:67], v[48:63]
	s_waitcnt lgkmcnt(0)
	v_mfma_f32_32x32x16_bf16 v[16:31], v[68:71], v[64:67], v[16:31]
	ds_read_b64_tr_b16 v[64:65], v152 offset:8704
	ds_read_b64_tr_b16 v[66:67], v152 offset:10880
	v_mul_f32_e64 v68, v72, v80
	v_mul_f32_e64 v69, v73, v80
	v_mul_f32_e64 v70, v82, v80
	v_mul_f32_e64 v71, v83, v80
	v_cvt_pk_bf16_f32 v68, v68, v69
	v_cvt_pk_bf16_f32 v69, v70, v71
	v_pk_mul_f32 v[70:71], v[86:87], v[80:81] op_sel_hi:[1,0]
	v_pk_mul_f32 v[72:73], v[92:93], v[80:81] op_sel_hi:[1,0]
	v_cvt_pk_bf16_f32 v70, v70, v71
	v_cvt_pk_bf16_f32 v71, v72, v73
	v_pk_mul_f32 v[72:73], v[102:103], v[80:81] op_sel_hi:[1,0]
	s_waitcnt lgkmcnt(0)
	v_mfma_f32_32x32x16_bf16 v[48:63], v[64:67], v[68:71], v[48:63]
	ds_read_b64_tr_b16 v[64:65], v152 offset:8768
	ds_read_b64_tr_b16 v[66:67], v152 offset:10944
	s_waitcnt lgkmcnt(0)
	v_mfma_f32_32x32x16_bf16 v[32:47], v[64:67], v[68:71], v[32:47]
	ds_read_b64_tr_b16 v[64:65], v152 offset:8832
	ds_read_b64_tr_b16 v[66:67], v152 offset:11008
	s_waitcnt lgkmcnt(0)
	v_mfma_f32_32x32x16_bf16 v[0:15], v[64:67], v[68:71], v[0:15]
	ds_read_b64_tr_b16 v[64:65], v152 offset:8896
	ds_read_b64_tr_b16 v[66:67], v152 offset:11072
	s_waitcnt lgkmcnt(0)
	v_mfma_f32_32x32x16_bf16 v[16:31], v[64:67], v[68:71], v[16:31]
	ds_read_b64_tr_b16 v[64:65], v152 offset:13056
	ds_read_b64_tr_b16 v[66:67], v152 offset:15232
	v_mul_f32_e64 v68, v88, v80
	v_mul_f32_e64 v69, v89, v80
	v_mul_f32_e64 v70, v94, v80
	v_mul_f32_e64 v71, v95, v80
	v_cvt_pk_bf16_f32 v68, v68, v69
	v_cvt_pk_bf16_f32 v69, v70, v71
	v_pk_mul_f32 v[70:71], v[96:97], v[80:81] op_sel_hi:[1,0]
	s_nop 0
	v_cvt_pk_bf16_f32 v70, v70, v71
	v_cvt_pk_bf16_f32 v71, v72, v73
	v_pk_mul_f32 v[72:73], v[112:113], v[80:81] op_sel_hi:[1,0]
	s_waitcnt lgkmcnt(0)
	v_mfma_f32_32x32x16_bf16 v[48:63], v[64:67], v[68:71], v[48:63]
	ds_read_b64_tr_b16 v[64:65], v152 offset:13120
	ds_read_b64_tr_b16 v[66:67], v152 offset:15296
	s_waitcnt lgkmcnt(0)
	v_mfma_f32_32x32x16_bf16 v[32:47], v[64:67], v[68:71], v[32:47]
	ds_read_b64_tr_b16 v[64:65], v152 offset:13184
	ds_read_b64_tr_b16 v[66:67], v152 offset:15360
	s_waitcnt lgkmcnt(0)
	v_mfma_f32_32x32x16_bf16 v[0:15], v[64:67], v[68:71], v[0:15]
	ds_read_b64_tr_b16 v[64:65], v152 offset:13248
	ds_read_b64_tr_b16 v[66:67], v152 offset:15424
	s_waitcnt lgkmcnt(0)
	v_mfma_f32_32x32x16_bf16 v[16:31], v[64:67], v[68:71], v[16:31]
	ds_read_b64_tr_b16 v[64:65], v152 offset:17408
	ds_read_b64_tr_b16 v[66:67], v152 offset:19584
	v_mul_f32_e64 v68, v100, v80
	v_mul_f32_e64 v69, v101, v80
	v_mul_f32_e64 v70, v104, v80
	v_mul_f32_e64 v71, v105, v80
	v_cvt_pk_bf16_f32 v68, v68, v69
	v_cvt_pk_bf16_f32 v69, v70, v71
	v_pk_mul_f32 v[70:71], v[108:109], v[80:81] op_sel_hi:[1,0]
	s_nop 0
	v_cvt_pk_bf16_f32 v70, v70, v71
	v_cvt_pk_bf16_f32 v71, v72, v73
	s_waitcnt lgkmcnt(0)
; #define LAS __attribute__((address_space(3)))
; __device__ __forceinline__ unsigned pk2(float lo, float hi) { const f32x2_t f = {lo, hi}; const bf16x2_t b = __builtin_convertvector(f, bf16x2_t); return __builtin_bit_cast(unsigned, b); }
; __device__ __forceinline__ void attn_item(const Params& P, int slice, int item, LAS unsigned char* lds) {
;     ...
; #pragma unroll
;   for (int kt = 0; kt < 5; ++kt)
; #pragma unroll
;     for (int s = 0; s < 2; ++s) {
;       u32x4 pb; pb.x = pk2(sc[kt][8 * s + 0] * inv, sc[kt][8 * s + 1] * inv); pb.y = pk2(sc[kt][8 * s + 2] * inv, sc[kt][8 * s + 3] * inv);
;       pb.z = pk2(sc[kt][8 * s + 4] * inv, sc[kt][8 * s + 5] * inv); pb.w = pk2(sc[kt][8 * s + 6] * inv, sc[kt][8 * s + 7] * inv);
;       const bf16x8 bfr = __builtin_bit_cast(bf16x8, pb);
;       const LAS unsigned char* vp = img + (32 * wq + 32 * kt + 16 * s + 4 * h + q4) * KROW + 2 * (16 * blk + 4 * p4);
; #pragma unroll
;       for (int dt = 0; dt < 4; ++dt) {
;         const s16x4 lo = __builtin_amdgcn_ds_read_tr16_b64_v4i16((LAS s16x4*)(vp + 64 * dt));
;         const s16x4 hi4 = __builtin_amdgcn_ds_read_tr16_b64_v4i16((LAS s16x4*)(vp + 64 * dt + 8 * KROW));
;         const bf16x8 a = __builtin_shufflevector(lo, hi4, 0, 1, 2, 3, 4, 5, 6, 7);
;         oa[dt] = __builtin_amdgcn_mfma_f32_32x32x16_bf16(a, bfr, oa[dt], 0, 0, 0);
;       }
;     }
	s_nop 0
	v_mfma_f32_32x32x16_bf16 v[48:63], v[64:67], v[68:71], v[48:63]
	ds_read_b64_tr_b16 v[64:65], v152 offset:17472
	ds_read_b64_tr_b16 v[66:67], v152 offset:19648
	s_waitcnt lgkmcnt(0)
	v_mfma_f32_32x32x16_bf16 v[32:47], v[64:67], v[68:71], v[32:47]
	ds_read_b64_tr_b16 v[64:65], v152 offset:17536
	ds_read_b64_tr_b16 v[66:67], v152 offset:19712
	ds_read_b64_tr_b16 v[72:73], v152 offset:17600
	ds_read_b64_tr_b16 v[74:75], v152 offset:19776
	ds_read_b64_tr_b16 v[76:77], v152 offset:21760
	ds_read_b64_tr_b16 v[78:79], v152 offset:23936
	s_waitcnt lgkmcnt(4)
	v_mfma_f32_32x32x16_bf16 v[0:15], v[64:67], v[68:71], v[0:15]
	v_mul_f32_e64 v64, v110, v80
	v_mul_f32_e64 v65, v111, v80
	v_mul_f32_e64 v66, v114, v80
	v_mul_f32_e64 v67, v115, v80
	v_cvt_pk_bf16_f32 v64, v64, v65
	v_cvt_pk_bf16_f32 v65, v66, v67
	v_pk_mul_f32 v[66:67], v[116:117], v[80:81] op_sel_hi:[1,0]
	s_nop 0
	v_cvt_pk_bf16_f32 v66, v66, v67
	s_waitcnt lgkmcnt(2)
	v_mfma_f32_32x32x16_bf16 v[16:31], v[72:75], v[68:71], v[16:31]
	v_mul_f32_e64 v68, v120, v80
	v_mul_f32_e64 v69, v121, v80
	v_cvt_pk_bf16_f32 v67, v68, v69
	ds_read_b64_tr_b16 v[68:69], v152 offset:21824
	ds_read_b64_tr_b16 v[70:71], v152 offset:24000
	ds_read_b64_tr_b16 v[72:73], v152 offset:21888
	s_waitcnt lgkmcnt(1)
	v_mfma_f32_32x32x16_bf16 v[32:47], v[68:71], v[64:67], v[32:47]
	ds_read_b64_tr_b16 v[74:75], v152 offset:24064
	ds_read_b64_tr_b16 v[68:69], v152 offset:21952
	ds_read_b64_tr_b16 v[70:71], v152 offset:24128
	v_mfma_f32_32x32x16_bf16 v[48:63], v[76:79], v[64:67], v[48:63]
	ds_read_b64_tr_b16 v[76:77], v152 offset:26112
	ds_read_b64_tr_b16 v[78:79], v152 offset:28288
	s_waitcnt lgkmcnt(4)
	v_mfma_f32_32x32x16_bf16 v[0:15], v[72:75], v[64:67], v[0:15]
	v_mul_f32_e64 v72, v118, v80
	v_mul_f32_e64 v73, v119, v80
	v_cvt_pk_bf16_f32 v72, v72, v73
	s_waitcnt lgkmcnt(2)
	v_mfma_f32_32x32x16_bf16 v[16:31], v[68:71], v[64:67], v[16:31]
	v_mul_f32_e64 v64, v122, v80
	v_mul_f32_e64 v65, v123, v80
	ds_read_b64_tr_b16 v[66:67], v152 offset:28352
	v_cvt_pk_bf16_f32 v73, v64, v65
	v_mul_f32_e64 v64, v124, v80
	v_mul_f32_e64 v65, v125, v80
	v_cvt_pk_bf16_f32 v74, v64, v65
	v_pk_mul_f32 v[64:65], v[128:129], v[80:81] op_sel_hi:[1,0]
	s_nop 0
	v_cvt_pk_bf16_f32 v75, v64, v65
	ds_read_b64_tr_b16 v[64:65], v152 offset:26176
	s_waitcnt lgkmcnt(2)
	v_mfma_f32_32x32x16_bf16 v[48:63], v[76:79], v[72:75], v[48:63]
	ds_read_b64_tr_b16 v[68:69], v152 offset:26240
	ds_read_b64_tr_b16 v[70:71], v152 offset:28416
	ds_read_b64_tr_b16 v[76:77], v152 offset:26304
	ds_read_b64_tr_b16 v[78:79], v152 offset:28480
	s_waitcnt lgkmcnt(2)
	v_mfma_f32_32x32x16_bf16 v[0:15], v[68:71], v[72:75], v[0:15]
	v_mul_f32_e64 v70, v138, v80
	v_mul_f32_e64 v71, v139, v80
	v_mfma_f32_32x32x16_bf16 v[32:47], v[64:67], v[72:75], v[32:47]
	v_mul_f32_e64 v64, v126, v80
	v_mul_f32_e64 v65, v127, v80
	ds_read_b64_tr_b16 v[66:67], v152 offset:30464
	ds_read_b64_tr_b16 v[68:69], v152 offset:32640
	ds_read_b64_tr_b16 v[82:83], v152 offset:30528
	ds_read_b64_tr_b16 v[84:85], v152 offset:32704
	ds_read_b64_tr_b16 v[94:95], v152 offset:30592
	ds_read_b64_tr_b16 v[96:97], v152 offset:32768
	v_cvt_pk_bf16_f32 v86, v64, v65
	v_pk_mul_f32 v[64:65], v[130:131], v[80:81] op_sel_hi:[1,0]
	s_nop 0
	v_cvt_pk_bf16_f32 v87, v64, v65
	v_pk_mul_f32 v[64:65], v[132:133], v[80:81] op_sel_hi:[1,0]
	s_waitcnt lgkmcnt(6)
	v_mfma_f32_32x32x16_bf16 v[16:31], v[76:79], v[72:75], v[16:31]
	v_cvt_pk_bf16_f32 v88, v64, v65
	v_mul_f32_e64 v64, v136, v80
	v_mul_f32_e64 v65, v137, v80
	ds_read_b64_tr_b16 v[76:77], v152 offset:30656
	ds_read_b64_tr_b16 v[78:79], v152 offset:32832
	v_cvt_pk_bf16_f32 v89, v64, v65
	v_pk_mul_f32 v[64:65], v[134:135], v[80:81] op_sel_hi:[1,0]
	ds_read_b64_tr_b16 v[102:103], v152 offset:34816
	ds_read_b64_tr_b16 v[104:105], v152 offset:36992
	ds_read_b64_tr_b16 v[90:91], v152 offset:34880
	ds_read_b64_tr_b16 v[92:93], v152 offset:37056
	v_cvt_pk_bf16_f32 v64, v64, v65
	s_waitcnt lgkmcnt(6)
; #define LAS __attribute__((address_space(3)))
; __device__ __forceinline__ unsigned pk2(float lo, float hi) { const f32x2_t f = {lo, hi}; const bf16x2_t b = __builtin_convertvector(f, bf16x2_t); return __builtin_bit_cast(unsigned, b); }
; __device__ __forceinline__ void attn_item(const Params& P, int slice, int item, LAS unsigned char* lds) {
;     ...
;       for (int dt = 0; dt < 4; ++dt) {
;         const s16x4 lo = __builtin_amdgcn_ds_read_tr16_b64_v4i16((LAS s16x4*)(vp + 64 * dt));
;         const s16x4 hi4 = __builtin_amdgcn_ds_read_tr16_b64_v4i16((LAS s16x4*)(vp + 64 * dt + 8 * KROW));
;         const bf16x8 a = __builtin_shufflevector(lo, hi4, 0, 1, 2, 3, 4, 5, 6, 7);
;         oa[dt] = __builtin_amdgcn_mfma_f32_32x32x16_bf16(a, bfr, oa[dt], 0, 0, 0);
;       }
;     }
;   u16* o3 = (u16*)(ws + O_O3) + ((size_t)gi * TS + tokq) * 512 + g * 128;
; #pragma unroll
;   for (int dt = 0; dt < 4; ++dt)
; #pragma unroll
;     for (int g4 = 0; g4 < 4; ++g4) {
;       u32x2 o; o.x = pk2(oa[dt][4 * g4], oa[dt][4 * g4 + 1]); o.y = pk2(oa[dt][4 * g4 + 2], oa[dt][4 * g4 + 3]);
;       *(u32x2*)(o3 + 32 * dt + 8 * g4 + 4 * h) = o;
;     }
	v_mfma_f32_32x32x16_bf16 v[0:15], v[94:97], v[86:89], v[0:15]
	v_cvt_pk_bf16_f32 v65, v70, v71
	v_mul_f32_e64 v70, v140, v80
	v_mul_f32_e64 v71, v141, v80
	v_mul_f32_e64 v94, v150, v80
	v_mul_f32_e64 v95, v151, v80
	v_mfma_f32_32x32x16_bf16 v[48:63], v[66:69], v[86:89], v[48:63]
	v_mul_f32_e64 v68, v144, v80
	v_mul_f32_e64 v69, v145, v80
	v_cvt_pk_bf16_f32 v66, v70, v71
	v_cvt_pk_bf16_f32 v67, v68, v69
	v_mul_f32_e64 v68, v142, v80
	v_mul_f32_e64 v69, v143, v80
	v_pk_mul_f32 v[70:71], v[146:147], v[80:81] op_sel_hi:[1,0]
	v_cvt_pk_bf16_f32 v68, v68, v69
	v_cvt_pk_bf16_f32 v69, v70, v71
	v_mfma_f32_32x32x16_bf16 v[32:47], v[82:85], v[86:89], v[32:47]
	ds_read_b64_tr_b16 v[82:83], v152 offset:34944
	ds_read_b64_tr_b16 v[84:85], v152 offset:37120
	ds_read_b64_tr_b16 v[72:73], v152 offset:35008
	ds_read_b64_tr_b16 v[74:75], v152 offset:37184
	v_mul_f32_e64 v70, v148, v80
	v_mul_f32_e64 v71, v149, v80
	ds_read_b64_tr_b16 v[98:99], v152 offset:39168
	ds_read_b64_tr_b16 v[100:101], v152 offset:41344
	v_cvt_pk_bf16_f32 v70, v70, v71
	v_cvt_pk_bf16_f32 v71, v94, v95
	v_lshlrev_b32_e32 v80, 1, v168
	s_waitcnt lgkmcnt(10)
	v_mfma_f32_32x32x16_bf16 v[16:31], v[76:79], v[86:89], v[16:31]
	ds_read_b64_tr_b16 v[94:95], v152 offset:39232
	ds_read_b64_tr_b16 v[96:97], v152 offset:41408
	ds_read_b64_tr_b16 v[86:87], v152 offset:39296
	ds_read_b64_tr_b16 v[88:89], v152 offset:41472
	ds_read_b64_tr_b16 v[76:77], v152 offset:39360
	ds_read_b64_tr_b16 v[78:79], v152 offset:41536
	s_waitcnt lgkmcnt(10)
	v_mfma_f32_32x32x16_bf16 v[0:15], v[82:85], v[64:67], v[0:15]
	v_mfma_f32_32x32x16_bf16 v[48:63], v[102:105], v[64:67], v[48:63]
	v_lshlrev_b64 v[102:103], 10, v[106:107]
	v_lshl_add_u64 v[102:103], s[0:1], 0, v[102:103]
	v_lshl_add_u64 v[102:103], v[102:103], 0, s[64:65]
	s_mov_b64 s[0:1], 0x2d852000
	v_mfma_f32_32x32x16_bf16 v[32:47], v[90:93], v[64:67], v[32:47]
	s_waitcnt lgkmcnt(8)
	v_mfma_f32_32x32x16_bf16 v[16:31], v[72:75], v[64:67], v[16:31]
	s_waitcnt lgkmcnt(2)
	v_mfma_f32_32x32x16_bf16 v[0:15], v[86:89], v[68:71], v[0:15]
	v_mfma_f32_32x32x16_bf16 v[48:63], v[98:101], v[68:71], v[48:63]
	v_lshl_add_u64 v[98:99], v[102:103], 0, v[80:81]
	v_lshl_add_u64 v[100:101], v[98:99], 0, s[0:1]
	v_mfma_f32_32x32x16_bf16 v[32:47], v[94:97], v[68:71], v[32:47]
	s_waitcnt lgkmcnt(0)
	v_mfma_f32_32x32x16_bf16 v[16:31], v[76:79], v[68:71], v[16:31]
	v_lshrrev_b32_e32 v102, 5, v225
	v_mov_b32_e32 v103, 0
	v_lshl_add_u64 v[100:101], v[102:103], 3, v[100:101]
	s_nop 4
	v_cvt_pk_bf16_f32 v0, v0, v1
	v_cvt_pk_bf16_f32 v1, v2, v3
	v_cvt_pk_bf16_f32 v2, v4, v5
	v_cvt_pk_bf16_f32 v3, v6, v7
	s_nop 1
	v_permlane32_swap_b32_e32 v0, v2
	v_permlane32_swap_b32_e32 v1, v3
	flat_store_dwordx4 v[100:101], v[0:3] offset:128
	v_cvt_pk_bf16_f32 v8, v8, v9
	v_cvt_pk_bf16_f32 v9, v10, v11
	v_cvt_pk_bf16_f32 v10, v12, v13
	v_cvt_pk_bf16_f32 v11, v14, v15
	s_nop 1
	v_permlane32_swap_b32_e32 v8, v10
	v_permlane32_swap_b32_e32 v9, v11
	flat_store_dwordx4 v[100:101], v[8:11] offset:160
	v_cvt_pk_bf16_f32 v48, v48, v49
	v_cvt_pk_bf16_f32 v49, v50, v51
	v_cvt_pk_bf16_f32 v50, v52, v53
	v_cvt_pk_bf16_f32 v51, v54, v55
	s_nop 1
	v_permlane32_swap_b32_e32 v48, v50
	v_permlane32_swap_b32_e32 v49, v51
	flat_store_dwordx4 v[100:101], v[48:51]
	v_cvt_pk_bf16_f32 v56, v56, v57
	v_cvt_pk_bf16_f32 v57, v58, v59
	v_cvt_pk_bf16_f32 v58, v60, v61
	v_cvt_pk_bf16_f32 v59, v62, v63
	s_nop 1
	v_permlane32_swap_b32_e32 v56, v58
	v_permlane32_swap_b32_e32 v57, v59
	flat_store_dwordx4 v[100:101], v[56:59] offset:32
	v_cvt_pk_bf16_f32 v32, v32, v33
	v_cvt_pk_bf16_f32 v33, v34, v35
	v_cvt_pk_bf16_f32 v34, v36, v37
	v_cvt_pk_bf16_f32 v35, v38, v39
	s_nop 1
	v_permlane32_swap_b32_e32 v32, v34
	v_permlane32_swap_b32_e32 v33, v35
	flat_store_dwordx4 v[100:101], v[32:35] offset:64
	v_cvt_pk_bf16_f32 v40, v40, v41
	v_cvt_pk_bf16_f32 v41, v42, v43
	v_cvt_pk_bf16_f32 v42, v44, v45
	v_cvt_pk_bf16_f32 v43, v46, v47
	s_nop 1
	v_permlane32_swap_b32_e32 v40, v42
	v_permlane32_swap_b32_e32 v41, v43
	flat_store_dwordx4 v[100:101], v[40:43] offset:96
	v_cvt_pk_bf16_f32 v16, v16, v17
	v_cvt_pk_bf16_f32 v17, v18, v19
	v_cvt_pk_bf16_f32 v18, v20, v21
	v_cvt_pk_bf16_f32 v19, v22, v23
	s_nop 1
	v_permlane32_swap_b32_e32 v16, v18
	v_permlane32_swap_b32_e32 v17, v19
	flat_store_dwordx4 v[100:101], v[16:19] offset:192
	v_cvt_pk_bf16_f32 v24, v24, v25
	v_cvt_pk_bf16_f32 v25, v26, v27
	v_cvt_pk_bf16_f32 v26, v28, v29
	v_cvt_pk_bf16_f32 v27, v30, v31
	s_nop 1
	v_permlane32_swap_b32_e32 v24, v26
	v_permlane32_swap_b32_e32 v25, v27
	flat_store_dwordx4 v[100:101], v[24:27] offset:224
	s_waitcnt lgkmcnt(0)
	s_barrier
